# combined: attention loop v3 + batched o_gla state loads + gate vectors parked in LDS in the out-proj epilogue + nt GEMM result stores + batched Q prologue and gate-rank loads
# speedup vs baseline: 1.0094x; 1.0053x over previous
; DI unsigned cvtpk(float lo, float hi) { f32x2_t v = {lo, hi}; bf16x2_t r = __builtin_convertvector(v, bf16x2_t); return __builtin_bit_cast(unsigned, r); }
; template <int EPI>
; DI void gemm_phase(const Params& p, char* lds, const bfu* __restrict__ A, const bfu* __restrict__ BT, int ntn, int l, const float* xin) {
;     ...
;     for (int rb = blockIdx.x * 8 + wave; rb < T / 16; rb += gridDim.x * 8) {
;       const bfu* hrow = A + (size_t)(rb * 16 + c16) * 1024 + quad * 8;
;       f32x4 c4 = {0.f, 0.f, 0.f, 0.f};
; #pragma unroll 8
;       for (int ks = 0; ks < 32; ++ks) {
;         const bf16x8 wf = *(const bf16x8*)(wrow + ks * 32);
;         const bf16x8 hf = *(const bf16x8*)(hrow + ks * 32);
;         c4 = __builtin_amdgcn_mfma_f32_16x16x32_bf16(wf, hf, c4, 0, 0, 0);
;       }
;       uint2 o; o.x = cvtpk(c4[0], c4[1]); o.y = cvtpk(c4[2], c4[3]);
;       *(uint2*)(proj + (size_t)(rb * 16 + c16) * NP + C_GLR + quad * 4) = o;
;     }
.LBB0_355:
	v_lshl_add_u64 v[14:15], v[4:5], 0, s[4:5]
	v_lshl_add_u64 v[18:19], v[10:11], 0, s[4:5]
	v_add_co_u32_e32 v22, vcc, 0x700000, v14
	s_add_u32 s4, s4, 0x200
	s_addc_u32 s5, s5, 0
	v_addc_co_u32_e32 v23, vcc, 0, v15, vcc
	v_add_co_u32_e32 v24, vcc, 0x26d8000, v18
	s_nop 1
	v_addc_co_u32_e32 v25, vcc, 0, v19, vcc
	s_cmpk_eq_i32 s4, 0x800
	global_load_dwordx4 v[32:35], v[22:23], off
	global_load_dwordx4 v[36:39], v[24:25], off offset:256
	global_load_dwordx4 v[40:43], v[22:23], off offset:64
	global_load_dwordx4 v[44:47], v[24:25], off offset:320
	global_load_dwordx4 v[48:51], v[22:23], off offset:128
	global_load_dwordx4 v[52:55], v[24:25], off offset:384
	global_load_dwordx4 v[56:59], v[22:23], off offset:192
	global_load_dwordx4 v[60:63], v[24:25], off offset:448
	global_load_dwordx4 v[64:67], v[22:23], off offset:256
	global_load_dwordx4 v[68:71], v[24:25], off offset:512
	global_load_dwordx4 v[72:75], v[22:23], off offset:320
	global_load_dwordx4 v[76:79], v[24:25], off offset:576
	global_load_dwordx4 v[80:83], v[22:23], off offset:384
	global_load_dwordx4 v[84:87], v[24:25], off offset:640
	global_load_dwordx4 v[88:91], v[22:23], off offset:448
	global_load_dwordx4 v[92:95], v[24:25], off offset:704
	s_waitcnt vmcnt(14)
	v_mfma_f32_16x16x32_bf16 v[0:3], v[32:35], v[36:39], v[0:3]
	s_waitcnt vmcnt(12)
	v_mfma_f32_16x16x32_bf16 v[0:3], v[40:43], v[44:47], v[0:3]
	s_waitcnt vmcnt(10)
	v_mfma_f32_16x16x32_bf16 v[0:3], v[48:51], v[52:55], v[0:3]
	s_waitcnt vmcnt(8)
	v_mfma_f32_16x16x32_bf16 v[0:3], v[56:59], v[60:63], v[0:3]
	s_waitcnt vmcnt(6)
	v_mfma_f32_16x16x32_bf16 v[0:3], v[64:67], v[68:71], v[0:3]
	s_waitcnt vmcnt(4)
	v_mfma_f32_16x16x32_bf16 v[0:3], v[72:75], v[76:79], v[0:3]
	s_waitcnt vmcnt(2)
	v_mfma_f32_16x16x32_bf16 v[0:3], v[80:83], v[84:87], v[0:3]
	s_waitcnt vmcnt(0)
	v_mfma_f32_16x16x32_bf16 v[0:3], v[88:91], v[92:95], v[0:3]
	s_cbranch_scc0 .LBB0_355
	v_lshl_or_b32 v9, s6, 4, v12
	s_nop 5
	v_cvt_pk_bf16_f32 v0, v0, v1
	v_cvt_pk_bf16_f32 v1, v2, v3
	v_mov_b64_e32 v[2:3], s[30:31]
	v_mad_i64_i32 v[2:3], s[4:5], v9, s0, v[2:3]
	v_lshl_add_u64 v[2:3], v[2:3], 0, v[196:197]
	v_add_co_u32_e32 v2, vcc, 0x66d9000, v2
	s_add_i32 s6, s6, s70
	s_nop 0
	v_addc_co_u32_e32 v3, vcc, 0, v3, vcc
	s_cmpk_gt_i32 s6, 0x7ff
	v_add_u32_e32 v8, s55, v8
	global_store_dwordx2 v[2:3], v[0:1], off offset:3328
	s_cbranch_scc0 .LBB0_354

; DI int pi_row(int r) { return (r & ~12) | ((r & 4) << 1) | ((r & 8) >> 1); }
; #define WAIT_BAR0() asm volatile("s_waitcnt vmcnt(0) lgkmcnt(0)\n\ts_barrier" ::: "memory")
; #define DMA_TILE(kt_, so_) do { glds16(kgp + (size_t)(kt_) * 64 * 128, dk0 + (so_)); glds16(kgp + (size_t)(kt_) * 64 * 128 + 32 * 128, dk0 + (so_) + 8192); \
;     glds16(vgp + (kt_) * 64, dk0 + (so_) + 16384); glds16(vgp + (size_t)64 * SEQ + (kt_) * 64, dk0 + (so_) + 24576); } while (0)
; DI void attn_item(const Params& p, char* lds, int l, int bh, int jt, float lam, float outscale) {
;     ...
;   const bfu* Kg = (const bfu*)(p.ws + WS_KN) + (size_t)bh * SEQ * 128;
;   const bfu* Qg = (const bfu*)(p.ws + WS_QN) + (size_t)bh * SEQ * 128;
;   const bfu* Vg = (const bfu*)(p.ws + WS_VT) + (size_t)bh * 128 * SEQ;
;   const int nkt = 4 * jt + 4, my_last = 4 * jt + (wave >> 1);
;   const int qrow = jt * 256 + wave * 32 + r;
;   const int krow_l = 4 * wave + (lane >> 4), kp = lane & 15;
;   const bfu* kgp = Kg + (size_t)krow_l * 128 + ((kp ^ (krow_l & 15)) * 8);
;   const int vrow_l = 8 * wave + (lane >> 3), vp = lane & 7;
;   const bfu* vgp = Vg + (size_t)vrow_l * SEQ + ((vp ^ ((vrow_l >> 1) & 7)) * 8);
;   const unsigned lds0 = (unsigned)(uintptr_t)lds;
;   const unsigned dk0 = (unsigned)__builtin_amdgcn_readfirstlane(lds0 + wave * 1024);
;     ...
;   WAIT_BAR0();
;   DMA_TILE(0, 0);
;   char* q1s = lds + 65536 + tid * 16;
; #pragma unroll
;   for (int ks = 0; ks < 4; ++ks) {
;     *(bf16x8*)(q1s + 32768 + ks * 8192) = *(const bf16x8*)(Qg + (size_t)qrow * 128 + ks * 16 + h * 8);
;     *(bf16x8*)(q1s + ks * 8192) = *(const bf16x8*)(Qg + (size_t)qrow * 128 + 64 + ks * 16 + h * 8);
;   }
;   f32x16 O0[4], O1[4];
; #pragma unroll
;   for (int d = 0; d < 4; ++d)
; #pragma unroll
;     for (int e = 0; e < 16; ++e) { O0[d][e] = 0.f; O1[d][e] = 0.f; }
;   float l0 = 0.f, l1 = 0.f;
;   const int pr = pi_row(r);
;   const unsigned kb = pr * 256 + (((pr & 15) ^ h) << 4);
;   const unsigned vb = 16384 + r * 128 + ((((r >> 1) & 7) ^ h) << 4);
.LBB0_723:
	s_and_b64 s[24:25], s[42:43], exec
	v_mov_b32_e32 v1, v199
	s_cselect_b32 s24, s23, s22
	v_readfirstlane_b32 s25, v1
	s_ashr_i32 s19, s25, 6
	s_lshl_b32 s26, s24, 8
	s_lshl_b32 s27, s19, 5
	s_add_i32 s27, s27, s26
	s_lshl_b32 s26, s19, 2
	v_bfe_u32 v2, v1, 4, 2
	v_bitop3_b32 v3, s26, v1, v2 bitop3:0x36
	v_or_b32_e32 v4, s26, v2
	v_lshlrev_b32_e32 v6, 4, v3
	v_ashrrev_i32_e32 v5, 31, v4
	v_and_b32_e32 v196, 0xf0, v6
	v_bfe_u32 v6, v1, 3, 3
	v_lshlrev_b64 v[4:5], 8, v[4:5]
	v_lshl_or_b32 v6, s19, 3, v6
	s_lshl_b32 s19, s19, 10
	v_and_b32_e32 v0, 31, v1
	v_lshl_add_u64 v[4:5], s[8:9], 0, v[4:5]
	s_cmp_lg_u32 0, -1
	v_or_b32_e32 v200, s27, v0
	v_lshl_add_u64 v[4:5], v[4:5], 0, v[196:197]
	v_ashrrev_i32_e32 v7, 31, v6
	s_cselect_b32 s27, 0, 0
	s_waitcnt vmcnt(0) lgkmcnt(0)
	s_barrier
	v_lshlrev_b64 v[8:9], 15, v[6:7]
	v_lshrrev_b32_e32 v6, 1, v6
	s_add_i32 s19, s19, s27
	s_mov_b32 s27, m0
	s_mov_b32 m0, s19
	s_nop 0
	global_load_lds_dwordx4 v[4:5], off
	s_mov_b32 m0, s27
	v_lshl_add_u64 v[4:5], v[4:5], 0, s[82:83]
	v_xor_b32_e32 v6, v6, v1
	s_add_i32 s27, s19, 0x2000
	s_mov_b32 s35, m0
	s_mov_b32 m0, s27
	s_nop 0
	global_load_lds_dwordx4 v[4:5], off
	s_mov_b32 m0, s35
	v_lshlrev_b32_e32 v4, 4, v1
	v_lshlrev_b32_e32 v6, 4, v6
	v_add_u32_e32 v4, 0, v4
	v_ashrrev_i32_e32 v201, 31, v200
	v_bfe_u32 v250, v1, 5, 1
	v_lshl_add_u64 v[8:9], s[12:13], 0, v[8:9]
	v_and_b32_e32 v196, 0x70, v6
	v_add_u32_e32 v251, 0x10000, v4
	v_lshlrev_b64 v[4:5], 8, v[200:201]
	v_lshl_add_u64 v[202:203], v[8:9], 0, v[196:197]
	s_add_i32 s27, s19, 0x4000
	s_mov_b32 s35, m0
	s_mov_b32 m0, s27
	s_nop 0
	global_load_lds_dwordx4 v[202:203], off
	s_mov_b32 m0, s35
	v_lshl_add_u64 v[4:5], s[10:11], 0, v[4:5]
	v_lshlrev_b32_e32 v196, 4, v250
	v_lshl_add_u64 v[204:205], v[202:203], 0, s[84:85]
	s_add_i32 s27, s19, 0x6000
	s_mov_b32 s35, m0
	s_mov_b32 m0, s27
	s_nop 0
	global_load_lds_dwordx4 v[204:205], off
	s_mov_b32 m0, s35
	v_subrev_u32_e32 v202, s12, v202
	v_lshl_add_u64 v[8:9], v[4:5], 0, v[196:197]
	global_load_dwordx4 v[10:13], v[8:9], off
	global_load_dwordx4 v[14:17], v[8:9], off offset:128
	global_load_dwordx4 v[18:21], v[8:9], off offset:32
	global_load_dwordx4 v[22:25], v[8:9], off offset:160
	global_load_dwordx4 v[26:29], v[8:9], off offset:64
	global_load_dwordx4 v[30:33], v[8:9], off offset:192
	global_load_dwordx4 v[34:37], v[8:9], off offset:96
	global_load_dwordx4 v[38:41], v[8:9], off offset:224
	s_cmp_lt_i32 s24, 0
	s_waitcnt vmcnt(7)
	ds_write_b128 v251, v[10:13] offset:32768
	s_waitcnt vmcnt(6)
	ds_write_b128 v251, v[14:17]
	s_waitcnt vmcnt(5)
	ds_write_b128 v251, v[18:21] offset:40960
	s_waitcnt vmcnt(4)
	ds_write_b128 v251, v[22:25] offset:8192
	s_waitcnt vmcnt(3)
	ds_write_b128 v251, v[26:29] offset:49152
	s_waitcnt vmcnt(2)
	ds_write_b128 v251, v[30:33] offset:16384
	s_waitcnt vmcnt(1)
	ds_write_b128 v251, v[34:37] offset:57344
	s_waitcnt vmcnt(0)
	ds_write_b128 v251, v[38:41] offset:24576
	s_cbranch_scc1 .LBB0_721
	v_and_b32_e32 v4, 19, v1
	v_lshrrev_b32_e32 v1, 1, v1
	v_lshlrev_b32_e32 v5, 1, v0
	v_and_b32_e32 v6, 4, v1
	v_lshlrev_b32_e32 v0, 7, v0
	v_bitop3_b32 v1, v1, v250, 7 bitop3:0x6c
	v_lshl_or_b32 v253, v1, 4, v0
	v_add_u32_e32 v0, s26, v2
	v_and_b32_e32 v5, 8, v5
	v_ashrrev_i32_e32 v1, 31, v0
	v_or3_b32 v4, v6, v4, v5
	v_lshlrev_b64 v[0:1], 8, v[0:1]
	v_and_b32_e32 v2, 15, v3
	s_lshl_b32 s27, s24, 2
	s_ashr_i32 s25, s25, 7
	v_lshlrev_b32_e32 v5, 8, v4
	v_bitop3_b32 v4, v4, v250, 15 bitop3:0x6c
	v_lshl_or_b32 v0, v2, 4, v0
	v_mov_b32_e32 v96, 0
	s_add_i32 s24, s27, 4
	s_add_i32 s25, s25, s27
	v_lshl_or_b32 v252, v4, 4, v5
	v_or_b32_e32 v237, 0x4000, v253
	v_lshl_add_u64 v[208:209], s[16:17], 0, v[0:1]
	v_subrev_u32_e32 v208, s16, v208
	s_mov_b32 s76, 64
	s_mov_b32 s26, 0
	s_mov_b32 s35, 0
	v_mov_b32_e32 v97, v96
	v_mov_b32_e32 v98, v96
	v_mov_b32_e32 v99, v96
	v_mov_b32_e32 v100, v96
	v_mov_b32_e32 v101, v96
	v_mov_b32_e32 v102, v96
	v_mov_b32_e32 v103, v96
	v_mov_b32_e32 v104, v96
	v_mov_b32_e32 v105, v96
	v_mov_b32_e32 v106, v96
	v_mov_b32_e32 v107, v96
	v_mov_b32_e32 v108, v96
	v_mov_b32_e32 v109, v96
	v_mov_b32_e32 v110, v96
	v_mov_b32_e32 v111, v96
	v_mov_b32_e32 v80, v96
	v_mov_b32_e32 v81, v96
	v_mov_b32_e32 v82, v96
	v_mov_b32_e32 v83, v96
	v_mov_b32_e32 v84, v96
	v_mov_b32_e32 v85, v96
	v_mov_b32_e32 v86, v96
	v_mov_b32_e32 v87, v96
	v_mov_b32_e32 v88, v96
	v_mov_b32_e32 v89, v96
	v_mov_b32_e32 v90, v96
	v_mov_b32_e32 v91, v96
	v_mov_b32_e32 v92, v96
	v_mov_b32_e32 v93, v96
	v_mov_b32_e32 v94, v96
	v_mov_b32_e32 v95, v96
	v_mov_b32_e32 v48, v96
	v_mov_b32_e32 v49, v96
	v_mov_b32_e32 v50, v96
	v_mov_b32_e32 v51, v96
	v_mov_b32_e32 v52, v96
	v_mov_b32_e32 v53, v96
	v_mov_b32_e32 v54, v96
	v_mov_b32_e32 v55, v96
	v_mov_b32_e32 v56, v96
	v_mov_b32_e32 v57, v96
	v_mov_b32_e32 v58, v96
	v_mov_b32_e32 v59, v96
	v_mov_b32_e32 v60, v96
	v_mov_b32_e32 v61, v96
	v_mov_b32_e32 v62, v96
	v_mov_b32_e32 v63, v96
	v_mov_b32_e32 v16, v96
	v_mov_b32_e32 v17, v96
	v_mov_b32_e32 v18, v96
	v_mov_b32_e32 v19, v96
	v_mov_b32_e32 v20, v96
	v_mov_b32_e32 v21, v96
	v_mov_b32_e32 v22, v96
	v_mov_b32_e32 v23, v96
	v_mov_b32_e32 v24, v96
	v_mov_b32_e32 v25, v96
	v_mov_b32_e32 v26, v96
	v_mov_b32_e32 v27, v96
	v_mov_b32_e32 v28, v96
	v_mov_b32_e32 v29, v96
	v_mov_b32_e32 v30, v96
	v_mov_b32_e32 v31, v96
	v_mov_b32_e32 v112, v96
	v_mov_b32_e32 v113, v96
	v_mov_b32_e32 v114, v96
	v_mov_b32_e32 v115, v96
	v_mov_b32_e32 v116, v96
	v_mov_b32_e32 v117, v96
	v_mov_b32_e32 v118, v96
	v_mov_b32_e32 v119, v96
	v_mov_b32_e32 v120, v96
	v_mov_b32_e32 v121, v96
	v_mov_b32_e32 v122, v96
	v_mov_b32_e32 v123, v96
	v_mov_b32_e32 v124, v96
	v_mov_b32_e32 v125, v96
	v_mov_b32_e32 v126, v96
	v_mov_b32_e32 v127, v96
	v_mov_b32_e32 v64, v96
	v_mov_b32_e32 v65, v96
	v_mov_b32_e32 v66, v96
	v_mov_b32_e32 v67, v96
	v_mov_b32_e32 v68, v96
	v_mov_b32_e32 v69, v96
	v_mov_b32_e32 v70, v96
	v_mov_b32_e32 v71, v96
	v_mov_b32_e32 v72, v96
	v_mov_b32_e32 v73, v96
	v_mov_b32_e32 v74, v96
	v_mov_b32_e32 v75, v96
	v_mov_b32_e32 v76, v96
	v_mov_b32_e32 v77, v96
	v_mov_b32_e32 v78, v96
	v_mov_b32_e32 v79, v96
	v_mov_b32_e32 v32, v96
	v_mov_b32_e32 v33, v96
	v_mov_b32_e32 v34, v96
	v_mov_b32_e32 v35, v96
	v_mov_b32_e32 v36, v96
	v_mov_b32_e32 v37, v96
	v_mov_b32_e32 v38, v96
	v_mov_b32_e32 v39, v96
	v_mov_b32_e32 v40, v96
	v_mov_b32_e32 v41, v96
	v_mov_b32_e32 v42, v96
	v_mov_b32_e32 v43, v96
	v_mov_b32_e32 v44, v96
	v_mov_b32_e32 v45, v96
	v_mov_b32_e32 v46, v96
	v_mov_b32_e32 v47, v96
	v_mov_b32_e32 v0, v96
	v_mov_b32_e32 v1, v96
	v_mov_b32_e32 v2, v96
	v_mov_b32_e32 v3, v96
	v_mov_b32_e32 v4, v96
	v_mov_b32_e32 v5, v96
	v_mov_b32_e32 v6, v96
	v_mov_b32_e32 v7, v96
	v_mov_b32_e32 v8, v96
	v_mov_b32_e32 v9, v96
	v_mov_b32_e32 v10, v96
	v_mov_b32_e32 v11, v96
	v_mov_b32_e32 v12, v96
	v_mov_b32_e32 v13, v96
	v_mov_b32_e32 v14, v96
	v_mov_b32_e32 v15, v96
	v_mov_b32_e32 v206, v96
	v_mov_b32_e32 v207, v96

; #define SBAR() __builtin_amdgcn_sched_barrier(0)
; template <int EPI>
; DI void gemm_phase(const Params& p, char* lds, const bfu* __restrict__ A, const bfu* __restrict__ BT, int ntn, int l, const float* xin) {
;     ...
;       for (int s = 0; s < 4; ++s) {
;         if (s < 3) {
;           const unsigned co = (unsigned)((((s + 1) * 2 + h) ^ swz) << 4);
;           af[(s + 1) & 1][0] = *(const bf16x8*)(pa + co); af[(s + 1) & 1][1] = *(const bf16x8*)(pa + 4096 + co);
; #pragma unroll
;           for (int j = 0; j < 4; ++j) bfr[(s + 1) & 1][j] = *(const bf16x8*)(pb + j * 4096 + co);
;         }
;         SBAR();
; #pragma unroll
;         for (int i = 0; i < 2; ++i)
; #pragma unroll
;           for (int j = 0; j < 4; ++j) {
;             acc[i][j] = MFMA32(bfr[s & 1][j], af[s & 1][i], acc[i][j]);
;             if (s < 2 && (j & 1) && dnext) DMA_PIECE(dA, dB, dk, dso, s * 4 + i * 2 + (j >> 1));
;           }
;         SBAR();
;       }
;     }
;     WAIT_BAR0();
;     ...
;       char* stg = lds + 65536 + wave * 8704;
;       const float* gate = (const float*)(p.ws + WS_MOD) + l * 6144 + (m0 >> 14) * 3072 + 2048;
;       float4 xn[8];
;     ...
;       LOADX(0);
; #pragma unroll
;       for (int ps = 0; ps < 4; ++ps) {
;         const int i = ps >> 1, jp = ps & 1;
;         float4 xc[8];
; #pragma unroll
;         for (int it = 0; it < 8; ++it) xc[it] = xn[it];
;         if (ps + 1 < 4) LOADX(ps + 1);
;         if (ps) WSYNC();
; #pragma unroll
;         for (int j2 = 0; j2 < 2; ++j2)
; #pragma unroll
;           for (int g = 0; g < 4; ++g) {
;             const f32x16& a = acc[i][2 * jp + j2];
;             float4 o; o.x = a[4 * g]; o.y = a[4 * g + 1]; o.z = a[4 * g + 2]; o.w = a[4 * g + 3];
;             *(float4*)(stg + r * 272 + (j2 * 32 + 8 * g + 4 * h) * 4) = o;
;           }
;         WSYNC();
; #pragma unroll
;         for (int it = 0; it < 8; ++it) {
;           const int id = it * 64 + lane, row = id >> 4, c = id & 15;
;           const float4 y = *(const float4*)(stg + row * 272 + c * 16);
;           const int m = m0 + wm * 64 + i * 32 + row, n = n0 + wn * 128 + jp * 64 + c * 4;
;           const float4 xv = xc[it];
;           const float4 gv = *(const float4*)(gate + n);
;           float4 o; o.x = xv.x + gv.x * y.x; o.y = xv.y + gv.y * y.y; o.z = xv.z + gv.z * y.z; o.w = xv.w + gv.w * y.w;
;           *(float4*)(p.out + (size_t)m * 1024 + n) = o;
;         }
.LBB0_801:
	v_add_u32_e32 v132, v209, v200
	v_add_u32_e32 v148, v210, v200
	ds_read_b128 v[128:131], v132
	ds_read_b128 v[132:135], v132 offset:4096
	ds_read_b128 v[136:139], v148 offset:32768
	ds_read_b128 v[140:143], v148 offset:36864
	ds_read_b128 v[144:147], v148 offset:40960
	ds_read_b128 v[148:151], v148 offset:45056
	s_waitcnt lgkmcnt(9)
	v_mfma_f32_32x32x16_bf16 v[112:127], v[172:175], v[164:167], v[112:127]
	s_waitcnt lgkmcnt(8)
	v_mfma_f32_32x32x16_bf16 v[96:111], v[168:171], v[164:167], v[96:111]
	s_waitcnt lgkmcnt(7)
	v_mfma_f32_32x32x16_bf16 v[80:95], v[160:163], v[164:167], v[80:95]
	s_waitcnt lgkmcnt(6)
	v_mfma_f32_32x32x16_bf16 v[64:79], v[156:159], v[164:167], v[64:79]
	v_mfma_f32_32x32x16_bf16 v[48:63], v[172:175], v[152:155], v[48:63]
	v_mfma_f32_32x32x16_bf16 v[32:47], v[168:171], v[152:155], v[32:47]
	v_mfma_f32_32x32x16_bf16 v[16:31], v[160:163], v[152:155], v[16:31]
	v_mfma_f32_32x32x16_bf16 v[0:15], v[156:159], v[152:155], v[0:15]
	s_waitcnt lgkmcnt(3)
	v_mfma_f32_32x32x16_bf16 v[112:127], v[136:139], v[128:131], v[112:127]
	s_waitcnt lgkmcnt(2)
	v_mfma_f32_32x32x16_bf16 v[96:111], v[140:143], v[128:131], v[96:111]
	s_waitcnt lgkmcnt(1)
	v_mfma_f32_32x32x16_bf16 v[80:95], v[144:147], v[128:131], v[80:95]
	s_waitcnt lgkmcnt(0)
	v_mfma_f32_32x32x16_bf16 v[64:79], v[148:151], v[128:131], v[64:79]
	v_mfma_f32_32x32x16_bf16 v[48:63], v[136:139], v[132:135], v[48:63]
	v_mfma_f32_32x32x16_bf16 v[32:47], v[140:143], v[132:135], v[32:47]
	v_mfma_f32_32x32x16_bf16 v[16:31], v[144:147], v[132:135], v[16:31]
	v_mfma_f32_32x32x16_bf16 v[0:15], v[148:151], v[132:135], v[0:15]
	s_lshr_b32 s4, s35, 6
	s_mulk_i32 s4, 0xc00
	s_ashr_i32 s5, s4, 31
	s_lshl_b64 s[4:5], s[4:5], 2
	s_add_u32 s4, s49, s4
	s_addc_u32 s5, s50, s5
	s_add_i32 s10, s10, s51
	v_or_b32_e32 v128, s10, v201
	v_ashrrev_i32_e32 v129, 31, v128
	v_lshlrev_b64 v[162:163], 12, v[128:129]
	v_or_b32_e32 v128, s10, v202
	v_ashrrev_i32_e32 v129, 31, v128
	v_lshlrev_b64 v[174:175], 12, v[128:129]
	v_or_b32_e32 v128, s10, v203
	v_ashrrev_i32_e32 v129, 31, v128
	v_lshlrev_b64 v[188:189], 12, v[128:129]
	v_or_b32_e32 v128, s10, v204
	v_or_b32_e32 v134, s10, v207
	v_ashrrev_i32_e32 v129, 31, v128
	v_ashrrev_i32_e32 v135, 31, v134
	v_lshlrev_b64 v[150:151], 12, v[128:129]
	v_or_b32_e32 v128, s10, v205
	v_or_b32_e32 v130, s10, v206
	v_lshlrev_b64 v[140:141], 12, v[134:135]
	v_or_b32_e32 v134, s10, v208
	s_waitcnt vmcnt(0) lgkmcnt(0)
	s_barrier
	v_ashrrev_i32_e32 v129, 31, v128
	v_ashrrev_i32_e32 v131, 31, v130
	v_ashrrev_i32_e32 v135, 31, v134
	ds_write_b128 v211, v[112:115]
	ds_write_b128 v211, v[116:119] offset:32
	ds_write_b128 v211, v[120:123] offset:64
	ds_write_b128 v211, v[124:127] offset:96
	ds_write_b128 v211, v[96:99] offset:128
	ds_write_b128 v211, v[100:103] offset:160
	ds_write_b128 v211, v[104:107] offset:192
	ds_write_b128 v211, v[108:111] offset:224
	v_or_b32_e32 v100, s8, v192
	v_lshl_add_u64 v[132:133], s[8:9], 2, v[178:179]
	v_lshlrev_b64 v[148:149], 12, v[128:129]
	v_lshlrev_b64 v[142:143], 12, v[130:131]
	v_lshlrev_b64 v[134:135], 12, v[134:135]
	s_add_u32 s4, s4, 0x26c2000
	v_ashrrev_i32_e32 v101, 31, v100
	v_lshl_add_u64 v[152:153], v[132:133], 0, v[174:175]
	v_lshl_add_u64 v[144:145], v[132:133], 0, v[188:189]
	v_lshl_add_u64 v[136:137], v[132:133], 0, v[150:151]
	v_lshl_add_u64 v[128:129], v[132:133], 0, v[148:149]
	v_lshl_add_u64 v[130:131], v[132:133], 0, v[142:143]
	v_lshl_add_u64 v[138:139], v[132:133], 0, v[140:141]
	v_lshl_add_u64 v[146:147], v[132:133], 0, v[134:135]
	s_addc_u32 s5, s5, 0
	v_lshlrev_b64 v[102:103], 2, v[100:101]
	v_lshl_add_u64 v[164:165], v[132:133], 0, v[162:163]
	v_lshl_add_u64 v[160:161], s[4:5], 0, v[102:103]
	global_load_dwordx4 v[96:99], v[146:147], off offset:256
	global_load_dwordx4 v[108:111], v[146:147], off
	global_load_dwordx4 v[104:107], v[138:139], off offset:256
	global_load_dwordx4 v[116:119], v[138:139], off
	global_load_dwordx4 v[112:115], v[130:131], off offset:256
	global_load_dwordx4 v[124:127], v[130:131], off
	global_load_dwordx4 v[120:123], v[128:129], off offset:256
	global_load_dwordx4 v[156:159], v[128:129], off
	s_nop 0
	global_load_dwordx4 v[128:131], v[136:137], off offset:256
	global_load_dwordx4 v[166:169], v[136:137], off
	s_nop 0
	global_load_dwordx4 v[136:139], v[144:145], off offset:256
	global_load_dwordx4 v[170:173], v[144:145], off
	s_nop 0
	global_load_dwordx4 v[144:147], v[152:153], off offset:256
	global_load_dwordx4 v[184:187], v[152:153], off
	s_nop 0
	global_load_dwordx4 v[152:155], v[164:165], off offset:256
	global_load_dwordx4 v[214:217], v[164:165], off
	s_waitcnt lgkmcnt(0)
	global_load_dwordx4 v[218:221], v[160:161], off
	ds_read_b128 v[222:225], v212
	ds_read_b128 v[226:229], v212 offset:1088
	v_lshl_add_u64 v[164:165], s[28:29], 0, v[102:103]
	v_lshl_add_u64 v[230:231], v[164:165], 0, v[162:163]
	s_or_b32 s8, s10, 32
	v_or_b32_e32 v100, 64, v100
	v_or_b32_e32 v102, s8, v201
	v_ashrrev_i32_e32 v101, 31, v100
	v_ashrrev_i32_e32 v103, 31, v102
	v_lshl_add_u64 v[162:163], v[100:101], 2, s[4:5]
	v_readlane_b32 s4, v255, 10
	s_add_i32 s66, s66, s4
	s_and_b64 vcc, exec, s[6:7]
	s_waitcnt vmcnt(0) lgkmcnt(1)
	v_pk_fma_f32 v[214:215], v[222:223], v[218:219], v[214:215]
	v_pk_fma_f32 v[216:217], v[224:225], v[220:221], v[216:217]
	global_store_dwordx4 v[230:231], v[214:217], off nt
	global_load_dwordx4 v[214:217], v[160:161], off
	v_lshl_add_u64 v[222:223], v[164:165], 0, v[174:175]
	v_lshl_add_u64 v[224:225], v[164:165], 0, v[188:189]
	v_lshlrev_b64 v[188:189], 12, v[102:103]
	ds_read_b128 v[218:221], v212 offset:3264
	s_waitcnt vmcnt(0) lgkmcnt(1)
; #define WSYNC() asm volatile("s_waitcnt lgkmcnt(0)" ::: "memory")
; #define LOADX(ps_) do { _Pragma("unroll") for (int it = 0; it < 8; ++it) { const int id = it * 64 + lane, row = id >> 4, c = id & 15; \
;           xn[it] = *(const float4*)(xin + (size_t)(m0 + wm * 64 + ((ps_) >> 1) * 32 + row) * 1024 + n0 + wn * 128 + ((ps_) & 1) * 64 + c * 4); } } while (0)
; template <int EPI>
; DI void gemm_phase(const Params& p, char* lds, const bfu* __restrict__ A, const bfu* __restrict__ BT, int ntn, int l, const float* xin) {
;     ...
;       for (int ps = 0; ps < 4; ++ps) {
;         const int i = ps >> 1, jp = ps & 1;
;         float4 xc[8];
; #pragma unroll
;         for (int it = 0; it < 8; ++it) xc[it] = xn[it];
;         if (ps + 1 < 4) LOADX(ps + 1);
;         if (ps) WSYNC();
; #pragma unroll
;         for (int j2 = 0; j2 < 2; ++j2)
; #pragma unroll
;           for (int g = 0; g < 4; ++g) {
;             const f32x16& a = acc[i][2 * jp + j2];
;             float4 o; o.x = a[4 * g]; o.y = a[4 * g + 1]; o.z = a[4 * g + 2]; o.w = a[4 * g + 3];
;             *(float4*)(stg + r * 272 + (j2 * 32 + 8 * g + 4 * h) * 4) = o;
;           }
;         WSYNC();
; #pragma unroll
;         for (int it = 0; it < 8; ++it) {
;           const int id = it * 64 + lane, row = id >> 4, c = id & 15;
;           const float4 y = *(const float4*)(stg + row * 272 + c * 16);
;           const int m = m0 + wm * 64 + i * 32 + row, n = n0 + wn * 128 + jp * 64 + c * 4;
;           const float4 xv = xc[it];
;           const float4 gv = *(const float4*)(gate + n);
;           float4 o; o.x = xv.x + gv.x * y.x; o.y = xv.y + gv.y * y.y; o.z = xv.z + gv.z * y.z; o.w = xv.w + gv.w * y.w;
;           *(float4*)(p.out + (size_t)m * 1024 + n) = o;
;         }
	v_pk_fma_f32 v[184:185], v[226:227], v[214:215], v[184:185]
	v_pk_fma_f32 v[186:187], v[228:229], v[216:217], v[186:187]
	global_store_dwordx4 v[222:223], v[184:187], off nt
	global_load_dwordx4 v[184:187], v[160:161], off
	ds_read_b128 v[214:217], v212 offset:2176
	v_lshl_add_u64 v[226:227], v[164:165], 0, v[134:135]
	v_lshl_add_u64 v[228:229], v[132:133], 0, v[188:189]
	s_waitcnt vmcnt(0) lgkmcnt(0)
	v_pk_fma_f32 v[170:171], v[214:215], v[184:185], v[170:171]
	v_pk_fma_f32 v[172:173], v[216:217], v[186:187], v[172:173]
	global_store_dwordx4 v[224:225], v[170:173], off nt
	global_load_dwordx4 v[170:173], v[160:161], off
	v_lshl_add_u64 v[214:215], v[164:165], 0, v[150:151]
	v_lshl_add_u64 v[216:217], v[164:165], 0, v[148:149]
	ds_read_b128 v[148:151], v212 offset:5440
	s_waitcnt vmcnt(0)
	v_pk_fma_f32 v[166:167], v[218:219], v[170:171], v[166:167]
	v_pk_fma_f32 v[168:169], v[220:221], v[172:173], v[168:169]
	global_store_dwordx4 v[214:215], v[166:169], off nt
	global_load_dwordx4 v[166:169], v[160:161], off
	ds_read_b128 v[170:173], v212 offset:4352
	v_lshl_add_u64 v[218:219], v[164:165], 0, v[142:143]
	v_lshl_add_u64 v[220:221], v[164:165], 0, v[140:141]
	ds_read_b128 v[140:143], v212 offset:7616
	s_waitcnt vmcnt(0) lgkmcnt(1)
	v_pk_fma_f32 v[156:157], v[170:171], v[166:167], v[156:157]
	v_pk_fma_f32 v[158:159], v[172:173], v[168:169], v[158:159]
	global_store_dwordx4 v[216:217], v[156:159], off nt
	global_load_dwordx4 v[156:159], v[160:161], off
	v_or_b32_e32 v166, s8, v208
	v_ashrrev_i32_e32 v167, 31, v166
	v_lshlrev_b64 v[166:167], 12, v[166:167]
	v_lshl_add_u64 v[236:237], v[132:133], 0, v[166:167]
	s_waitcnt vmcnt(0)
	v_pk_fma_f32 v[124:125], v[148:149], v[156:157], v[124:125]
	v_pk_fma_f32 v[126:127], v[150:151], v[158:159], v[126:127]
	global_store_dwordx4 v[218:219], v[124:127], off nt
	global_load_dwordx4 v[124:127], v[160:161], off
	ds_read_b128 v[148:151], v212 offset:6528
	v_or_b32_e32 v156, s8, v206
	v_or_b32_e32 v158, s8, v207
	v_ashrrev_i32_e32 v157, 31, v156
	v_ashrrev_i32_e32 v159, 31, v158
	v_lshlrev_b64 v[170:171], 12, v[156:157]
	v_lshlrev_b64 v[168:169], 12, v[158:159]
	v_lshl_add_u64 v[250:251], v[132:133], 0, v[170:171]
	v_lshl_add_u64 v[252:253], v[132:133], 0, v[168:169]
	s_waitcnt vmcnt(0) lgkmcnt(0)
	v_pk_fma_f32 v[116:117], v[148:149], v[124:125], v[116:117]
	v_pk_fma_f32 v[118:119], v[150:151], v[126:127], v[118:119]
	global_store_dwordx4 v[220:221], v[116:119], off nt
	global_load_dwordx4 v[116:119], v[160:161], off
	v_or_b32_e32 v124, s8, v202
	v_or_b32_e32 v126, s8, v203
	v_or_b32_e32 v148, s8, v204
	v_or_b32_e32 v150, s8, v205
	v_ashrrev_i32_e32 v125, 31, v124
	v_ashrrev_i32_e32 v127, 31, v126
	v_ashrrev_i32_e32 v149, 31, v148
	v_ashrrev_i32_e32 v151, 31, v150
	v_lshlrev_b64 v[186:187], 12, v[124:125]
	v_lshlrev_b64 v[184:185], 12, v[126:127]
	v_lshlrev_b64 v[174:175], 12, v[148:149]
	v_lshlrev_b64 v[172:173], 12, v[150:151]
	v_lshl_add_u64 v[232:233], v[132:133], 0, v[186:187]
	v_lshl_add_u64 v[240:241], v[132:133], 0, v[184:185]
	v_lshl_add_u64 v[242:243], v[132:133], 0, v[174:175]
	v_lshl_add_u64 v[248:249], v[132:133], 0, v[172:173]
	s_waitcnt vmcnt(0)
	v_pk_fma_f32 v[100:101], v[140:141], v[116:117], v[108:109]
	v_pk_fma_f32 v[102:103], v[142:143], v[118:119], v[110:111]
	global_store_dwordx4 v[226:227], v[100:103], off nt
	global_load_dwordx4 v[100:103], v[236:237], off
	s_nop 0
	global_load_dwordx4 v[108:111], v[252:253], off
	global_load_dwordx4 v[116:119], v[250:251], off
	global_load_dwordx4 v[124:127], v[248:249], off
	global_load_dwordx4 v[132:135], v[242:243], off
	global_load_dwordx4 v[140:143], v[240:241], off
	global_load_dwordx4 v[148:151], v[232:233], off
	global_load_dwordx4 v[156:159], v[228:229], off
	s_waitcnt lgkmcnt(0)
	ds_write_b128 v211, v[80:83]
	ds_write_b128 v211, v[84:87] offset:32
	ds_write_b128 v211, v[88:91] offset:64
	ds_write_b128 v211, v[92:95] offset:96
	ds_write_b128 v211, v[64:67] offset:128
	ds_write_b128 v211, v[68:71] offset:160
	ds_write_b128 v211, v[72:75] offset:192
	ds_write_b128 v211, v[76:79] offset:224
	s_waitcnt lgkmcnt(0)
	global_load_dwordx4 v[64:67], v[162:163], off
	v_lshlrev_b32_e32 v246, 5, v199
	v_add_u32_e32 v246, 0x22080, v246
	ds_read_b128 v[68:71], v212
	ds_read_b128 v[72:75], v212 offset:1088
	s_waitcnt vmcnt(0) lgkmcnt(1)
	ds_write_b128 v246, v[64:67] offset:16
	v_pk_fma_f32 v[64:65], v[68:69], v[64:65], v[152:153]
	v_pk_fma_f32 v[66:67], v[70:71], v[66:67], v[154:155]
	global_store_dwordx4 v[230:231], v[64:67], off offset:256 nt
	s_nop 0
	ds_read_b128 v[64:67], v246 offset:16
	s_waitcnt lgkmcnt(0)
	v_pk_fma_f32 v[64:65], v[72:73], v[64:65], v[144:145]
	v_pk_fma_f32 v[66:67], v[74:75], v[66:67], v[146:147]
	global_store_dwordx4 v[222:223], v[64:67], off offset:256 nt
	s_nop 0
	ds_read_b128 v[64:67], v246 offset:16
	ds_read_b128 v[68:71], v212 offset:2176
	ds_read_b128 v[72:75], v212 offset:3264
	s_waitcnt lgkmcnt(1)
	v_pk_fma_f32 v[64:65], v[68:69], v[64:65], v[136:137]
	v_pk_fma_f32 v[66:67], v[70:71], v[66:67], v[138:139]
	global_store_dwordx4 v[224:225], v[64:67], off offset:256 nt
	s_nop 0
	ds_read_b128 v[64:67], v246 offset:16
	s_waitcnt lgkmcnt(0)
	v_pk_fma_f32 v[64:65], v[72:73], v[64:65], v[128:129]
	v_pk_fma_f32 v[66:67], v[74:75], v[66:67], v[130:131]
	global_store_dwordx4 v[214:215], v[64:67], off offset:256 nt
	s_nop 0
	ds_read_b128 v[64:67], v246 offset:16
	ds_read_b128 v[68:71], v212 offset:4352
	ds_read_b128 v[72:75], v212 offset:5440
	s_waitcnt lgkmcnt(1)
	v_pk_fma_f32 v[64:65], v[68:69], v[64:65], v[120:121]
	v_pk_fma_f32 v[66:67], v[70:71], v[66:67], v[122:123]
	global_store_dwordx4 v[216:217], v[64:67], off offset:256 nt
	s_nop 0
	ds_read_b128 v[64:67], v246 offset:16
	s_waitcnt lgkmcnt(0)
; #define WSYNC() asm volatile("s_waitcnt lgkmcnt(0)" ::: "memory")
; #define LOADX(ps_) do { _Pragma("unroll") for (int it = 0; it < 8; ++it) { const int id = it * 64 + lane, row = id >> 4, c = id & 15; \
;           xn[it] = *(const float4*)(xin + (size_t)(m0 + wm * 64 + ((ps_) >> 1) * 32 + row) * 1024 + n0 + wn * 128 + ((ps_) & 1) * 64 + c * 4); } } while (0)
; template <int EPI>
; DI void gemm_phase(const Params& p, char* lds, const bfu* __restrict__ A, const bfu* __restrict__ BT, int ntn, int l, const float* xin) {
;     ...
;       for (int ps = 0; ps < 4; ++ps) {
;         const int i = ps >> 1, jp = ps & 1;
;         float4 xc[8];
; #pragma unroll
;         for (int it = 0; it < 8; ++it) xc[it] = xn[it];
;         if (ps + 1 < 4) LOADX(ps + 1);
;         if (ps) WSYNC();
; #pragma unroll
;         for (int j2 = 0; j2 < 2; ++j2)
; #pragma unroll
;           for (int g = 0; g < 4; ++g) {
;             const f32x16& a = acc[i][2 * jp + j2];
;             float4 o; o.x = a[4 * g]; o.y = a[4 * g + 1]; o.z = a[4 * g + 2]; o.w = a[4 * g + 3];
;             *(float4*)(stg + r * 272 + (j2 * 32 + 8 * g + 4 * h) * 4) = o;
;           }
;         WSYNC();
; #pragma unroll
;         for (int it = 0; it < 8; ++it) {
;           const int id = it * 64 + lane, row = id >> 4, c = id & 15;
;           const float4 y = *(const float4*)(stg + row * 272 + c * 16);
;           const int m = m0 + wm * 64 + i * 32 + row, n = n0 + wn * 128 + jp * 64 + c * 4;
;           const float4 xv = xc[it];
;           const float4 gv = *(const float4*)(gate + n);
;           float4 o; o.x = xv.x + gv.x * y.x; o.y = xv.y + gv.y * y.y; o.z = xv.z + gv.z * y.z; o.w = xv.w + gv.w * y.w;
;           *(float4*)(p.out + (size_t)m * 1024 + n) = o;
;         }
	v_pk_fma_f32 v[64:65], v[72:73], v[64:65], v[112:113]
	v_pk_fma_f32 v[66:67], v[74:75], v[66:67], v[114:115]
	global_store_dwordx4 v[218:219], v[64:67], off offset:256 nt
	s_nop 0
	ds_read_b128 v[64:67], v246 offset:16
	ds_read_b128 v[68:71], v212 offset:6528
	ds_read_b128 v[72:75], v212 offset:7616
	s_waitcnt lgkmcnt(1)
	v_pk_fma_f32 v[64:65], v[68:69], v[64:65], v[104:105]
	v_pk_fma_f32 v[66:67], v[70:71], v[66:67], v[106:107]
	global_store_dwordx4 v[220:221], v[64:67], off offset:256 nt
	s_nop 0
	ds_read_b128 v[64:67], v246 offset:16
	s_waitcnt lgkmcnt(0)
	v_pk_fma_f32 v[64:65], v[72:73], v[64:65], v[96:97]
	v_pk_fma_f32 v[66:67], v[74:75], v[66:67], v[98:99]
	global_store_dwordx4 v[226:227], v[64:67], off offset:256 nt
	global_load_dwordx4 v[64:67], v[236:237], off offset:256
	s_nop 0
	global_load_dwordx4 v[68:71], v[252:253], off offset:256
	global_load_dwordx4 v[72:75], v[250:251], off offset:256
	global_load_dwordx4 v[76:79], v[248:249], off offset:256
	global_load_dwordx4 v[80:83], v[242:243], off offset:256
	global_load_dwordx4 v[84:87], v[240:241], off offset:256
	global_load_dwordx4 v[88:91], v[232:233], off offset:256
	global_load_dwordx4 v[92:95], v[228:229], off offset:256
	s_waitcnt lgkmcnt(0)
	ds_write_b128 v211, v[48:51]
	ds_write_b128 v211, v[52:55] offset:32
	ds_write_b128 v211, v[56:59] offset:64
	ds_write_b128 v211, v[60:63] offset:96
	ds_write_b128 v211, v[32:35] offset:128
	ds_write_b128 v211, v[36:39] offset:160
	ds_write_b128 v211, v[40:43] offset:192
	ds_write_b128 v211, v[44:47] offset:224
	s_waitcnt lgkmcnt(0)
	global_load_dwordx4 v[32:35], v[160:161], off
	ds_read_b128 v[36:39], v212
	ds_read_b128 v[40:43], v212 offset:1088
	v_lshl_add_u64 v[44:45], v[164:165], 0, v[188:189]
	v_lshl_add_u64 v[46:47], v[164:165], 0, v[186:187]
	v_lshl_add_u64 v[48:49], v[164:165], 0, v[184:185]
	v_lshl_add_u64 v[50:51], v[164:165], 0, v[174:175]
	v_lshl_add_u64 v[52:53], v[164:165], 0, v[172:173]
	v_lshl_add_u64 v[54:55], v[164:165], 0, v[170:171]
	v_lshl_add_u64 v[56:57], v[164:165], 0, v[168:169]
	s_waitcnt vmcnt(0) lgkmcnt(1)
	ds_write_b128 v246, v[32:35]
	v_pk_fma_f32 v[32:33], v[36:37], v[32:33], v[156:157]
	v_pk_fma_f32 v[34:35], v[38:39], v[34:35], v[158:159]
	global_store_dwordx4 v[44:45], v[32:35], off nt
	s_nop 0
	ds_read_b128 v[32:35], v246
	ds_read_b128 v[36:39], v212 offset:2176
	s_waitcnt lgkmcnt(1)
	v_pk_fma_f32 v[32:33], v[40:41], v[32:33], v[148:149]
	v_pk_fma_f32 v[34:35], v[42:43], v[34:35], v[150:151]
	global_store_dwordx4 v[46:47], v[32:35], off nt
	s_nop 0
	ds_read_b128 v[32:35], v246
	ds_read_b128 v[40:43], v212 offset:3264
	s_waitcnt lgkmcnt(1)
	v_pk_fma_f32 v[32:33], v[36:37], v[32:33], v[140:141]
	v_pk_fma_f32 v[34:35], v[38:39], v[34:35], v[142:143]
	global_store_dwordx4 v[48:49], v[32:35], off nt
	s_nop 0
	ds_read_b128 v[32:35], v246
	ds_read_b128 v[36:39], v212 offset:4352
	s_waitcnt lgkmcnt(1)
	v_pk_fma_f32 v[32:33], v[40:41], v[32:33], v[132:133]
	v_pk_fma_f32 v[34:35], v[42:43], v[34:35], v[134:135]
	global_store_dwordx4 v[50:51], v[32:35], off nt
	s_nop 0
	ds_read_b128 v[32:35], v246
	ds_read_b128 v[40:43], v212 offset:5440
	s_waitcnt lgkmcnt(1)
	v_pk_fma_f32 v[32:33], v[36:37], v[32:33], v[124:125]
	v_pk_fma_f32 v[34:35], v[38:39], v[34:35], v[126:127]
	global_store_dwordx4 v[52:53], v[32:35], off nt
	s_nop 0
	ds_read_b128 v[32:35], v246
	ds_read_b128 v[36:39], v212 offset:6528
	s_waitcnt lgkmcnt(1)
	v_pk_fma_f32 v[32:33], v[40:41], v[32:33], v[116:117]
	v_pk_fma_f32 v[34:35], v[42:43], v[34:35], v[118:119]
	global_store_dwordx4 v[54:55], v[32:35], off nt
	s_nop 0
	ds_read_b128 v[32:35], v246
	ds_read_b128 v[40:43], v212 offset:7616
	s_waitcnt lgkmcnt(1)
	v_pk_fma_f32 v[32:33], v[36:37], v[32:33], v[108:109]
	v_pk_fma_f32 v[34:35], v[38:39], v[34:35], v[110:111]
	global_store_dwordx4 v[56:57], v[32:35], off nt
	s_nop 0
	ds_read_b128 v[32:35], v246
	v_lshl_add_u64 v[36:37], v[164:165], 0, v[166:167]
	s_waitcnt lgkmcnt(0)
	v_pk_fma_f32 v[32:33], v[40:41], v[32:33], v[100:101]
	v_pk_fma_f32 v[34:35], v[42:43], v[34:35], v[102:103]
	global_store_dwordx4 v[36:37], v[32:35], off nt
	s_waitcnt lgkmcnt(0)
	ds_write_b128 v211, v[16:19]
	ds_write_b128 v211, v[20:23] offset:32
	ds_write_b128 v211, v[24:27] offset:64
	ds_write_b128 v211, v[28:31] offset:96
	ds_write_b128 v211, v[0:3] offset:128
	ds_write_b128 v211, v[4:7] offset:160
	ds_write_b128 v211, v[8:11] offset:192
	ds_write_b128 v211, v[12:15] offset:224
	s_waitcnt lgkmcnt(0)
	s_nop 0
	ds_read_b128 v[0:3], v246 offset:16
	ds_read_b128 v[4:7], v212
	ds_read_b128 v[8:11], v212 offset:1088
	s_waitcnt vmcnt(0) lgkmcnt(1)
	v_pk_fma_f32 v[0:1], v[4:5], v[0:1], v[92:93]
	v_pk_fma_f32 v[2:3], v[6:7], v[2:3], v[94:95]
	global_store_dwordx4 v[44:45], v[0:3], off offset:256 nt
	s_nop 0
	ds_read_b128 v[0:3], v246 offset:16
	s_waitcnt lgkmcnt(0)
	v_pk_fma_f32 v[0:1], v[8:9], v[0:1], v[88:89]
	v_pk_fma_f32 v[2:3], v[10:11], v[2:3], v[90:91]
	global_store_dwordx4 v[46:47], v[0:3], off offset:256 nt
	s_nop 0
	ds_read_b128 v[0:3], v246 offset:16
	ds_read_b128 v[4:7], v212 offset:2176
	ds_read_b128 v[8:11], v212 offset:3264
	s_waitcnt lgkmcnt(1)
	v_pk_fma_f32 v[0:1], v[4:5], v[0:1], v[84:85]
	v_pk_fma_f32 v[2:3], v[6:7], v[2:3], v[86:87]
	global_store_dwordx4 v[48:49], v[0:3], off offset:256 nt
	s_nop 0
	ds_read_b128 v[0:3], v246 offset:16
	s_waitcnt lgkmcnt(0)
	v_pk_fma_f32 v[0:1], v[8:9], v[0:1], v[80:81]
	v_pk_fma_f32 v[2:3], v[10:11], v[2:3], v[82:83]
	global_store_dwordx4 v[50:51], v[0:3], off offset:256 nt
	s_nop 0
	ds_read_b128 v[0:3], v246 offset:16
	ds_read_b128 v[4:7], v212 offset:4352
	ds_read_b128 v[8:11], v212 offset:5440
	s_waitcnt lgkmcnt(1)
	v_pk_fma_f32 v[0:1], v[4:5], v[0:1], v[76:77]
	v_pk_fma_f32 v[2:3], v[6:7], v[2:3], v[78:79]
	global_store_dwordx4 v[52:53], v[0:3], off offset:256 nt
	s_nop 0
	ds_read_b128 v[0:3], v246 offset:16
	s_waitcnt lgkmcnt(0)
	v_pk_fma_f32 v[0:1], v[8:9], v[0:1], v[72:73]
	v_pk_fma_f32 v[2:3], v[10:11], v[2:3], v[74:75]
	global_store_dwordx4 v[54:55], v[0:3], off offset:256 nt
	s_nop 0
	ds_read_b128 v[0:3], v246 offset:16
	ds_read_b128 v[4:7], v212 offset:6528
	ds_read_b128 v[8:11], v212 offset:7616
	s_waitcnt lgkmcnt(1)
	v_pk_fma_f32 v[0:1], v[4:5], v[0:1], v[68:69]
	v_pk_fma_f32 v[2:3], v[6:7], v[2:3], v[70:71]
	global_store_dwordx4 v[56:57], v[0:3], off offset:256 nt
	s_nop 0
	ds_read_b128 v[0:3], v246 offset:16
	s_waitcnt lgkmcnt(0)
	v_pk_fma_f32 v[0:1], v[8:9], v[0:1], v[64:65]
	v_pk_fma_f32 v[2:3], v[10:11], v[2:3], v[66:67]
	global_store_dwordx4 v[36:37], v[0:3], off offset:256 nt
	s_cbranch_vccnz .LBB0_822

; __global__ void __launch_bounds__(NT) fwd_megakernel(Params p) {
;   extern __shared__ __attribute__((aligned(16))) char lds[];
	.amdhsa_kernel _Z14fwd_megakernel6Params
		.amdhsa_group_segment_fixed_size 16512
		.amdhsa_private_segment_fixed_size 0
		.amdhsa_kernarg_size 440
		.amdhsa_user_sgpr_count 2
		.amdhsa_user_sgpr_dispatch_ptr 0
		.amdhsa_user_sgpr_queue_ptr 0
		.amdhsa_user_sgpr_kernarg_segment_ptr 1
		.amdhsa_user_sgpr_dispatch_id 0
		.amdhsa_user_sgpr_kernarg_preload_length 0
		.amdhsa_user_sgpr_kernarg_preload_offset 0
		.amdhsa_user_sgpr_private_segment_size 0
		.amdhsa_uses_dynamic_stack 0
		.amdhsa_enable_private_segment 0
		.amdhsa_system_sgpr_workgroup_id_x 1
		.amdhsa_system_sgpr_workgroup_id_y 0
		.amdhsa_system_sgpr_workgroup_id_z 0
		.amdhsa_system_sgpr_workgroup_info 0
		.amdhsa_system_vgpr_workitem_id 2
		.amdhsa_next_free_vgpr 256
		.amdhsa_next_free_sgpr 100
		.amdhsa_accum_offset 256
		.amdhsa_reserve_vcc 1
		.amdhsa_float_round_mode_32 0
		.amdhsa_float_round_mode_16_64 0
		.amdhsa_float_denorm_mode_32 3
		.amdhsa_float_denorm_mode_16_64 3
		.amdhsa_dx10_clamp 1
		.amdhsa_ieee_mode 1
		.amdhsa_fp16_overflow 0
		.amdhsa_tg_split 0
		.amdhsa_exception_fp_ieee_invalid_op 0
		.amdhsa_exception_fp_denorm_src 0
		.amdhsa_exception_fp_ieee_div_zero 0
		.amdhsa_exception_fp_ieee_overflow 0
		.amdhsa_exception_fp_ieee_underflow 0
		.amdhsa_exception_fp_ieee_inexact 0
		.amdhsa_exception_int_div_zero 0
	.end_amdhsa_kernel

; __global__ void __launch_bounds__(NT) fwd_megakernel(Params p) {
;   extern __shared__ __attribute__((aligned(16))) char lds[];
amdhsa.kernels:
  - .agpr_count:     0
    .args:
      - .offset:         0
        .size:           184
        .value_kind:     by_value
      - .offset:         184
        .size:           4
        .value_kind:     hidden_block_count_x
      - .offset:         188
        .size:           4
        .value_kind:     hidden_block_count_y
      - .offset:         192
        .size:           4
        .value_kind:     hidden_block_count_z
      - .offset:         196
        .size:           2
        .value_kind:     hidden_group_size_x
      - .offset:         198
        .size:           2
        .value_kind:     hidden_group_size_y
      - .offset:         200
        .size:           2
        .value_kind:     hidden_group_size_z
      - .offset:         202
        .size:           2
        .value_kind:     hidden_remainder_x
      - .offset:         204
        .size:           2
        .value_kind:     hidden_remainder_y
      - .offset:         206
        .size:           2
        .value_kind:     hidden_remainder_z
      - .offset:         224
        .size:           8
        .value_kind:     hidden_global_offset_x
      - .offset:         232
        .size:           8
        .value_kind:     hidden_global_offset_y
      - .offset:         240
        .size:           8
        .value_kind:     hidden_global_offset_z
      - .offset:         248
        .size:           2
        .value_kind:     hidden_grid_dims
      - .offset:         272
        .size:           8
        .value_kind:     hidden_multigrid_sync_arg
      - .offset:         304
        .size:           4
        .value_kind:     hidden_dynamic_lds_size
    .group_segment_fixed_size: 16512
    .kernarg_segment_align: 8
    .kernarg_segment_size: 440
    .language:       OpenCL C
    .language_version:
      - 2
      - 0
    .max_flat_workgroup_size: 512
    .name:           _Z14fwd_megakernel6Params
    .private_segment_fixed_size: 0
    .sgpr_count:     106
    .sgpr_spill_count: 132
    .symbol:         _Z14fwd_megakernel6Params.kd
    .uniform_work_group_size: 1
    .uses_dynamic_stack: false
    .vgpr_count:     256
    .vgpr_spill_count: 0
    .wavefront_size: 64
